# mix-phase weight conversion: eight load pairs per iteration issued before one wait (was pair, wait, write eight times)
# baseline (speedup 1.0000x reference)
.LBB0_137:
	s_lshl_b32 s11, s8, 1
	s_lshl_b32 s10, s1, 1
	v_or_b32_e32 v0, s11, v24
	v_or_b32_e32 v30, s10, v7
	v_mov_b32_e32 v31, v1
	v_lshlrev_b64 v[32:33], 12, v[0:1]
	v_lshlrev_b64 v[30:31], 12, v[30:31]
	v_lshl_add_u64 v[32:33], v[22:23], 0, v[32:33]
	v_lshl_add_u64 v[30:31], v[22:23], 0, v[30:31]
	global_load_dword v40, v[32:33], off
	global_load_dword v41, v[30:31], off
	v_or_b32_e32 v34, s10, v3
	v_or_b32_e32 v35, s11, v2
	v_mad_u64_u32 v[178:179], s[12:13], v35, s53, v[6:7]
	v_mad_u64_u32 v[180:181], s[12:13], v34, s53, v[6:7]
	s_add_i32 s13, s11, 4
	s_add_i32 s12, s10, 4
	v_mov_b32_e32 v31, v1
	v_or_b32_e32 v34, s12, v3
	v_or_b32_e32 v35, s13, v2
	s_add_i32 s8, s8, 16
	s_add_i32 s1, s1, 16
	s_add_i32 s9, s9, -16
	v_or_b32_e32 v0, s13, v24
	v_or_b32_e32 v30, s12, v7
	v_lshlrev_b64 v[32:33], 12, v[0:1]
	v_lshlrev_b64 v[30:31], 12, v[30:31]
	v_lshl_add_u64 v[32:33], v[22:23], 0, v[32:33]
	v_lshl_add_u64 v[30:31], v[22:23], 0, v[30:31]
	global_load_dword v42, v[32:33], off
	global_load_dword v43, v[30:31], off
	v_mad_u64_u32 v[182:183], s[12:13], v35, s53, v[6:7]
	v_mad_u64_u32 v[184:185], s[12:13], v34, s53, v[6:7]
	s_add_i32 s13, s11, 8
	s_add_i32 s12, s10, 8
	v_mov_b32_e32 v31, v1
	v_or_b32_e32 v34, s12, v3
	v_or_b32_e32 v35, s13, v2
	v_or_b32_e32 v0, s13, v24
	v_or_b32_e32 v30, s12, v7
	v_lshlrev_b64 v[32:33], 12, v[0:1]
	v_lshlrev_b64 v[30:31], 12, v[30:31]
	v_lshl_add_u64 v[32:33], v[22:23], 0, v[32:33]
	v_lshl_add_u64 v[30:31], v[22:23], 0, v[30:31]
	global_load_dword v44, v[32:33], off
	global_load_dword v45, v[30:31], off
	v_mad_u64_u32 v[186:187], s[12:13], v35, s53, v[6:7]
	v_mad_u64_u32 v[188:189], s[12:13], v34, s53, v[6:7]
	s_add_i32 s13, s11, 12
	s_add_i32 s12, s10, 12
	v_mov_b32_e32 v31, v1
	v_or_b32_e32 v34, s12, v3
	v_or_b32_e32 v35, s13, v2
	v_or_b32_e32 v0, s13, v24
	v_or_b32_e32 v30, s12, v7
	v_lshlrev_b64 v[32:33], 12, v[0:1]
	v_lshlrev_b64 v[30:31], 12, v[30:31]
	v_lshl_add_u64 v[32:33], v[22:23], 0, v[32:33]
	v_lshl_add_u64 v[30:31], v[22:23], 0, v[30:31]
	global_load_dword v46, v[32:33], off
	global_load_dword v47, v[30:31], off
	v_mad_u64_u32 v[190:191], s[12:13], v35, s53, v[6:7]
	v_mad_u64_u32 v[192:193], s[12:13], v34, s53, v[6:7]
	s_add_i32 s13, s11, 16
	s_add_i32 s12, s10, 16
	v_mov_b32_e32 v31, v1
	v_or_b32_e32 v34, s12, v3
	v_or_b32_e32 v35, s13, v2
	v_or_b32_e32 v0, s13, v24
	v_or_b32_e32 v30, s12, v7
	v_lshlrev_b64 v[32:33], 12, v[0:1]
	v_lshlrev_b64 v[30:31], 12, v[30:31]
	v_lshl_add_u64 v[32:33], v[22:23], 0, v[32:33]
	v_lshl_add_u64 v[30:31], v[22:23], 0, v[30:31]
	global_load_dword v48, v[32:33], off
	global_load_dword v49, v[30:31], off
	v_mad_u64_u32 v[194:195], s[12:13], v35, s53, v[6:7]
	v_mad_u64_u32 v[196:197], s[12:13], v34, s53, v[6:7]
	s_add_i32 s13, s11, 20
	s_add_i32 s12, s10, 20
	v_mov_b32_e32 v31, v1
	v_or_b32_e32 v34, s12, v3
	v_or_b32_e32 v35, s13, v2
	v_or_b32_e32 v0, s13, v24
	v_or_b32_e32 v30, s12, v7
	v_lshlrev_b64 v[32:33], 12, v[0:1]
	v_lshlrev_b64 v[30:31], 12, v[30:31]
	v_lshl_add_u64 v[32:33], v[22:23], 0, v[32:33]
	v_lshl_add_u64 v[30:31], v[22:23], 0, v[30:31]
	global_load_dword v50, v[32:33], off
	global_load_dword v51, v[30:31], off
	v_mad_u64_u32 v[198:199], s[12:13], v35, s53, v[6:7]
	v_mad_u64_u32 v[200:201], s[12:13], v34, s53, v[6:7]
	s_add_i32 s13, s11, 24
	s_add_i32 s12, s10, 24
	v_mov_b32_e32 v31, v1
	v_or_b32_e32 v35, s13, v2
	v_or_b32_e32 v34, s12, v3
	s_add_i32 s11, s11, 28
	s_add_i32 s10, s10, 28
	s_cmp_lg_u32 s9, 0
	v_or_b32_e32 v0, s13, v24
	v_or_b32_e32 v30, s12, v7
	v_lshlrev_b64 v[32:33], 12, v[0:1]
	v_lshlrev_b64 v[30:31], 12, v[30:31]
	v_lshl_add_u64 v[32:33], v[22:23], 0, v[32:33]
	v_lshl_add_u64 v[30:31], v[22:23], 0, v[30:31]
	global_load_dword v52, v[32:33], off
	global_load_dword v53, v[30:31], off
	v_mad_u64_u32 v[202:203], s[12:13], v35, s53, v[6:7]
	v_mad_u64_u32 v[204:205], s[12:13], v34, s53, v[6:7]
	v_mov_b32_e32 v31, v1
	v_or_b32_e32 v35, s11, v2
	v_or_b32_e32 v34, s10, v3
	v_or_b32_e32 v0, s11, v24
	v_or_b32_e32 v30, s10, v7
	v_lshlrev_b64 v[32:33], 12, v[0:1]
	v_lshlrev_b64 v[30:31], 12, v[30:31]
	v_lshl_add_u64 v[32:33], v[22:23], 0, v[32:33]
	v_lshl_add_u64 v[30:31], v[22:23], 0, v[30:31]
	global_load_dword v54, v[32:33], off
	global_load_dword v55, v[30:31], off
	v_mad_u64_u32 v[206:207], s[10:11], v35, s53, v[6:7]
	v_mad_u64_u32 v[208:209], s[10:11], v34, s53, v[6:7]
	s_waitcnt vmcnt(0)
	ds_write_b32 v178, v40
	ds_write_b32 v180, v41
	ds_write_b32 v182, v42
	ds_write_b32 v184, v43
	ds_write_b32 v186, v44
	ds_write_b32 v188, v45
	ds_write_b32 v190, v46
	ds_write_b32 v192, v47
	ds_write_b32 v194, v48
	ds_write_b32 v196, v49
	ds_write_b32 v198, v50
	ds_write_b32 v200, v51
	ds_write_b32 v202, v52
	ds_write_b32 v204, v53
	ds_write_b32 v206, v54
	ds_write_b32 v208, v55
	s_cbranch_scc1 .LBB0_137
	s_waitcnt lgkmcnt(0)
	ds_read_b32 v0, v26
	ds_read_b32 v7, v26 offset:132
	s_lshl_b32 s88, s5, 1
	v_lshl_add_u64 v[22:23], v[10:11], 0, s[88:89]
	s_movk_i32 s88, 0xf400
	s_waitcnt lgkmcnt(0)
	v_cvt_pk_bf16_f32 v30, v0, v7
	ds_read_b32 v0, v26 offset:264
	ds_read_b32 v7, v26 offset:396
	s_waitcnt lgkmcnt(0)
	v_cvt_pk_bf16_f32 v31, v0, v7
	ds_read_b32 v0, v26 offset:528
	ds_read_b32 v7, v26 offset:660
	s_waitcnt lgkmcnt(0)
	v_cvt_pk_bf16_f32 v32, v0, v7
	ds_read_b32 v0, v26 offset:792
	ds_read_b32 v7, v26 offset:924
	s_waitcnt lgkmcnt(0)
	v_cvt_pk_bf16_f32 v33, v0, v7
	v_or_b32_e32 v0, s0, v25
	v_lshlrev_b32_e32 v0, 13, v0
	v_lshl_add_u64 v[34:35], v[22:23], 0, v[0:1]
	flat_store_dwordx4 v[34:35], v[30:33]
	ds_read_b32 v0, v26 offset:32
	ds_read_b32 v7, v26 offset:164
	s_waitcnt lgkmcnt(0)
	v_cvt_pk_bf16_f32 v30, v0, v7
	ds_read_b32 v0, v26 offset:296
	ds_read_b32 v7, v26 offset:428
	s_waitcnt lgkmcnt(0)
	v_cvt_pk_bf16_f32 v31, v0, v7
	ds_read_b32 v0, v26 offset:560
	ds_read_b32 v7, v26 offset:692
	s_waitcnt lgkmcnt(0)
	v_cvt_pk_bf16_f32 v32, v0, v7
	ds_read_b32 v0, v26 offset:824
	ds_read_b32 v7, v26 offset:956
	s_waitcnt lgkmcnt(0)
	v_cvt_pk_bf16_f32 v33, v0, v7
	v_or_b32_e32 v0, s0, v27
	v_lshlrev_b32_e32 v0, 13, v0
	v_lshl_add_u64 v[34:35], v[22:23], 0, v[0:1]
	flat_store_dwordx4 v[34:35], v[30:33]
	ds_read_b32 v0, v26 offset:64
	ds_read_b32 v7, v26 offset:196
	s_waitcnt lgkmcnt(0)
	v_cvt_pk_bf16_f32 v30, v0, v7
	ds_read_b32 v0, v26 offset:328
	ds_read_b32 v7, v26 offset:460
	s_waitcnt lgkmcnt(0)
	v_cvt_pk_bf16_f32 v31, v0, v7
	ds_read_b32 v0, v26 offset:592
	ds_read_b32 v7, v26 offset:724
	s_waitcnt lgkmcnt(0)
	v_cvt_pk_bf16_f32 v32, v0, v7
	ds_read_b32 v0, v26 offset:856
	ds_read_b32 v7, v26 offset:988
	s_waitcnt lgkmcnt(0)
	v_cvt_pk_bf16_f32 v33, v0, v7
	v_or_b32_e32 v0, s0, v28
	v_lshlrev_b32_e32 v0, 13, v0
	v_lshl_add_u64 v[34:35], v[22:23], 0, v[0:1]
	flat_store_dwordx4 v[34:35], v[30:33]
	ds_read_b32 v0, v26 offset:96
	ds_read_b32 v7, v26 offset:228
	s_waitcnt lgkmcnt(0)
	v_cvt_pk_bf16_f32 v30, v0, v7
	ds_read_b32 v0, v26 offset:360
	ds_read_b32 v7, v26 offset:492
	s_waitcnt lgkmcnt(0)
	v_cvt_pk_bf16_f32 v31, v0, v7
	ds_read_b32 v0, v26 offset:624
	ds_read_b32 v7, v26 offset:756
	s_waitcnt lgkmcnt(0)
	v_cvt_pk_bf16_f32 v32, v0, v7
	ds_read_b32 v0, v26 offset:888
	ds_read_b32 v7, v26 offset:1020
	s_waitcnt lgkmcnt(0)
	v_cvt_pk_bf16_f32 v33, v0, v7
	v_or_b32_e32 v0, s0, v29
	v_lshlrev_b32_e32 v0, 13, v0
	v_lshl_add_u64 v[22:23], v[22:23], 0, v[0:1]
	flat_store_dwordx4 v[22:23], v[30:33]
	s_waitcnt lgkmcnt(0)
	s_mov_b64 s[0:1], 0

.LBB0_141:
	s_lshl_b32 s10, s4, 1
	s_lshl_b32 s9, s5, 1
	v_or_b32_e32 v0, s10, v24
	v_or_b32_e32 v30, s9, v7
	v_mov_b32_e32 v31, v1
	v_lshlrev_b64 v[32:33], 14, v[0:1]
	v_lshlrev_b64 v[30:31], 14, v[30:31]
	v_lshl_add_u64 v[32:33], v[22:23], 0, v[32:33]
	v_lshl_add_u64 v[30:31], v[22:23], 0, v[30:31]
	global_load_dword v40, v[32:33], off
	global_load_dword v41, v[30:31], off
	v_or_b32_e32 v34, s9, v3
	v_or_b32_e32 v35, s10, v2
	v_mad_u64_u32 v[178:179], s[12:13], v35, s53, v[6:7]
	v_mad_u64_u32 v[180:181], s[12:13], v34, s53, v[6:7]
	s_add_i32 s12, s10, 4
	s_add_i32 s11, s9, 4
	v_mov_b32_e32 v31, v1
	v_or_b32_e32 v34, s11, v3
	v_or_b32_e32 v35, s12, v2
	s_add_i32 s4, s4, 16
	s_add_i32 s5, s5, 16
	s_add_i32 s8, s8, -16
	v_or_b32_e32 v0, s12, v24
	v_or_b32_e32 v30, s11, v7
	v_lshlrev_b64 v[32:33], 14, v[0:1]
	v_lshlrev_b64 v[30:31], 14, v[30:31]
	v_lshl_add_u64 v[32:33], v[22:23], 0, v[32:33]
	v_lshl_add_u64 v[30:31], v[22:23], 0, v[30:31]
	global_load_dword v42, v[32:33], off
	global_load_dword v43, v[30:31], off
	v_mad_u64_u32 v[182:183], s[12:13], v35, s53, v[6:7]
	v_mad_u64_u32 v[184:185], s[12:13], v34, s53, v[6:7]
	s_add_i32 s12, s10, 8
	s_add_i32 s11, s9, 8
	v_mov_b32_e32 v31, v1
	v_or_b32_e32 v34, s11, v3
	v_or_b32_e32 v35, s12, v2
	v_or_b32_e32 v0, s12, v24
	v_or_b32_e32 v30, s11, v7
	v_lshlrev_b64 v[32:33], 14, v[0:1]
	v_lshlrev_b64 v[30:31], 14, v[30:31]
	v_lshl_add_u64 v[32:33], v[22:23], 0, v[32:33]
	v_lshl_add_u64 v[30:31], v[22:23], 0, v[30:31]
	global_load_dword v44, v[32:33], off
	global_load_dword v45, v[30:31], off
	v_mad_u64_u32 v[186:187], s[12:13], v35, s53, v[6:7]
	v_mad_u64_u32 v[188:189], s[12:13], v34, s53, v[6:7]
	s_add_i32 s12, s10, 12
	s_add_i32 s11, s9, 12
	v_mov_b32_e32 v31, v1
	v_or_b32_e32 v34, s11, v3
	v_or_b32_e32 v35, s12, v2
	v_or_b32_e32 v0, s12, v24
	v_or_b32_e32 v30, s11, v7
	v_lshlrev_b64 v[32:33], 14, v[0:1]
	v_lshlrev_b64 v[30:31], 14, v[30:31]
	v_lshl_add_u64 v[32:33], v[22:23], 0, v[32:33]
	v_lshl_add_u64 v[30:31], v[22:23], 0, v[30:31]
	global_load_dword v46, v[32:33], off
	global_load_dword v47, v[30:31], off
	v_mad_u64_u32 v[190:191], s[12:13], v35, s53, v[6:7]
	v_mad_u64_u32 v[192:193], s[12:13], v34, s53, v[6:7]
	s_add_i32 s12, s10, 16
	s_add_i32 s11, s9, 16
	v_mov_b32_e32 v31, v1
	v_or_b32_e32 v34, s11, v3
	v_or_b32_e32 v35, s12, v2
	v_or_b32_e32 v0, s12, v24
	v_or_b32_e32 v30, s11, v7
	v_lshlrev_b64 v[32:33], 14, v[0:1]
	v_lshlrev_b64 v[30:31], 14, v[30:31]
	v_lshl_add_u64 v[32:33], v[22:23], 0, v[32:33]
	v_lshl_add_u64 v[30:31], v[22:23], 0, v[30:31]
	global_load_dword v48, v[32:33], off
	global_load_dword v49, v[30:31], off
	v_mad_u64_u32 v[194:195], s[12:13], v35, s53, v[6:7]
	v_mad_u64_u32 v[196:197], s[12:13], v34, s53, v[6:7]
	s_add_i32 s12, s10, 20
	s_add_i32 s11, s9, 20
	v_mov_b32_e32 v31, v1
	v_or_b32_e32 v34, s11, v3
	v_or_b32_e32 v35, s12, v2
	v_or_b32_e32 v0, s12, v24
	v_or_b32_e32 v30, s11, v7
	v_lshlrev_b64 v[32:33], 14, v[0:1]
	v_lshlrev_b64 v[30:31], 14, v[30:31]
	v_lshl_add_u64 v[32:33], v[22:23], 0, v[32:33]
	v_lshl_add_u64 v[30:31], v[22:23], 0, v[30:31]
	global_load_dword v50, v[32:33], off
	global_load_dword v51, v[30:31], off
	v_mad_u64_u32 v[198:199], s[12:13], v35, s53, v[6:7]
	v_mad_u64_u32 v[200:201], s[12:13], v34, s53, v[6:7]
	s_add_i32 s12, s10, 24
	s_add_i32 s11, s9, 24
	v_mov_b32_e32 v31, v1
	v_or_b32_e32 v35, s12, v2
	v_or_b32_e32 v34, s11, v3
	s_add_i32 s10, s10, 28
	s_add_i32 s9, s9, 28
	s_cmp_lg_u32 s8, 0
	v_or_b32_e32 v0, s12, v24
	v_or_b32_e32 v30, s11, v7
	v_lshlrev_b64 v[32:33], 14, v[0:1]
	v_lshlrev_b64 v[30:31], 14, v[30:31]
	v_lshl_add_u64 v[32:33], v[22:23], 0, v[32:33]
	v_lshl_add_u64 v[30:31], v[22:23], 0, v[30:31]
	global_load_dword v52, v[32:33], off
	global_load_dword v53, v[30:31], off
	v_mad_u64_u32 v[202:203], s[12:13], v35, s53, v[6:7]
	v_mad_u64_u32 v[204:205], s[12:13], v34, s53, v[6:7]
	v_mov_b32_e32 v31, v1
	v_or_b32_e32 v35, s10, v2
	v_or_b32_e32 v34, s9, v3
	v_or_b32_e32 v0, s10, v24
	v_or_b32_e32 v30, s9, v7
	v_lshlrev_b64 v[32:33], 14, v[0:1]
	v_lshlrev_b64 v[30:31], 14, v[30:31]
	v_lshl_add_u64 v[32:33], v[22:23], 0, v[32:33]
	v_lshl_add_u64 v[30:31], v[22:23], 0, v[30:31]
	global_load_dword v54, v[32:33], off
	global_load_dword v55, v[30:31], off
	v_mad_u64_u32 v[206:207], s[10:11], v35, s53, v[6:7]
	v_mad_u64_u32 v[208:209], s[10:11], v34, s53, v[6:7]
	s_waitcnt vmcnt(0)
	ds_write_b32 v178, v40
	ds_write_b32 v180, v41
	ds_write_b32 v182, v42
	ds_write_b32 v184, v43
	ds_write_b32 v186, v44
	ds_write_b32 v188, v45
	ds_write_b32 v190, v46
	ds_write_b32 v192, v47
	ds_write_b32 v194, v48
	ds_write_b32 v196, v49
	ds_write_b32 v198, v50
	ds_write_b32 v200, v51
	ds_write_b32 v202, v52
	ds_write_b32 v204, v53
	ds_write_b32 v206, v54
	ds_write_b32 v208, v55
	s_cbranch_scc1 .LBB0_141
	s_waitcnt lgkmcnt(0)
	ds_read_b32 v0, v26
	ds_read_b32 v7, v26 offset:132
	s_lshl_b32 s88, s1, 1
	v_lshl_add_u64 v[22:23], v[14:15], 0, s[88:89]
	s_movk_i32 s88, 0xf400
	s_waitcnt lgkmcnt(0)
	v_cvt_pk_bf16_f32 v30, v0, v7
	ds_read_b32 v0, v26 offset:264
	ds_read_b32 v7, v26 offset:396
	s_waitcnt lgkmcnt(0)
	v_cvt_pk_bf16_f32 v31, v0, v7
	ds_read_b32 v0, v26 offset:528
	ds_read_b32 v7, v26 offset:660
	s_waitcnt lgkmcnt(0)
	v_cvt_pk_bf16_f32 v32, v0, v7
	ds_read_b32 v0, v26 offset:792
	ds_read_b32 v7, v26 offset:924
	s_waitcnt lgkmcnt(0)
	v_cvt_pk_bf16_f32 v33, v0, v7
	v_or_b32_e32 v0, s0, v25
	v_lshlrev_b32_e32 v0, 11, v0
	v_lshl_add_u64 v[34:35], v[22:23], 0, v[0:1]
	flat_store_dwordx4 v[34:35], v[30:33]
	ds_read_b32 v0, v26 offset:32
	ds_read_b32 v7, v26 offset:164
	s_waitcnt lgkmcnt(0)
	v_cvt_pk_bf16_f32 v30, v0, v7
	ds_read_b32 v0, v26 offset:296
	ds_read_b32 v7, v26 offset:428
	s_waitcnt lgkmcnt(0)
	v_cvt_pk_bf16_f32 v31, v0, v7
	ds_read_b32 v0, v26 offset:560
	ds_read_b32 v7, v26 offset:692
	s_waitcnt lgkmcnt(0)
	v_cvt_pk_bf16_f32 v32, v0, v7
	ds_read_b32 v0, v26 offset:824
	ds_read_b32 v7, v26 offset:956
	s_waitcnt lgkmcnt(0)
	v_cvt_pk_bf16_f32 v33, v0, v7
	v_or_b32_e32 v0, s0, v27
	v_lshlrev_b32_e32 v0, 11, v0
	v_lshl_add_u64 v[34:35], v[22:23], 0, v[0:1]
	flat_store_dwordx4 v[34:35], v[30:33]
	ds_read_b32 v0, v26 offset:64
	ds_read_b32 v7, v26 offset:196
	s_waitcnt lgkmcnt(0)
	v_cvt_pk_bf16_f32 v30, v0, v7
	ds_read_b32 v0, v26 offset:328
	ds_read_b32 v7, v26 offset:460
	s_waitcnt lgkmcnt(0)
	v_cvt_pk_bf16_f32 v31, v0, v7
	ds_read_b32 v0, v26 offset:592
	ds_read_b32 v7, v26 offset:724
	s_waitcnt lgkmcnt(0)
	v_cvt_pk_bf16_f32 v32, v0, v7
	ds_read_b32 v0, v26 offset:856
	ds_read_b32 v7, v26 offset:988
	s_waitcnt lgkmcnt(0)
	v_cvt_pk_bf16_f32 v33, v0, v7
	v_or_b32_e32 v0, s0, v28
	v_lshlrev_b32_e32 v0, 11, v0
	v_lshl_add_u64 v[34:35], v[22:23], 0, v[0:1]
	flat_store_dwordx4 v[34:35], v[30:33]
	ds_read_b32 v0, v26 offset:96
	ds_read_b32 v7, v26 offset:228
	s_waitcnt lgkmcnt(0)
	v_cvt_pk_bf16_f32 v30, v0, v7
	ds_read_b32 v0, v26 offset:360
	ds_read_b32 v7, v26 offset:492
	s_waitcnt lgkmcnt(0)
	v_cvt_pk_bf16_f32 v31, v0, v7
	ds_read_b32 v0, v26 offset:624
	ds_read_b32 v7, v26 offset:756
	s_waitcnt lgkmcnt(0)
	v_cvt_pk_bf16_f32 v32, v0, v7
	ds_read_b32 v0, v26 offset:888
	ds_read_b32 v7, v26 offset:1020
	s_waitcnt lgkmcnt(0)
	v_cvt_pk_bf16_f32 v33, v0, v7
	v_or_b32_e32 v0, s0, v29
	v_lshlrev_b32_e32 v0, 11, v0
	v_lshl_add_u64 v[22:23], v[22:23], 0, v[0:1]
	flat_store_dwordx4 v[22:23], v[30:33]
	s_waitcnt lgkmcnt(0)

.LBB0_146:
	s_lshl_b32 s10, s5, 1
	s_lshl_b32 s9, s1, 1
	v_or_b32_e32 v0, s10, v24
	v_or_b32_e32 v30, s9, v7
	v_mov_b32_e32 v31, v1
	v_lshlrev_b64 v[32:33], 12, v[0:1]
	v_lshlrev_b64 v[30:31], 12, v[30:31]
	v_lshl_add_u64 v[32:33], v[22:23], 0, v[32:33]
	v_lshl_add_u64 v[30:31], v[22:23], 0, v[30:31]
	global_load_dword v40, v[32:33], off
	global_load_dword v41, v[30:31], off
	v_or_b32_e32 v34, s9, v3
	v_or_b32_e32 v35, s10, v2
	v_mad_u64_u32 v[178:179], s[12:13], v35, s53, v[6:7]
	v_mad_u64_u32 v[180:181], s[12:13], v34, s53, v[6:7]
	s_add_i32 s12, s10, 4
	s_add_i32 s11, s9, 4
	v_mov_b32_e32 v31, v1
	v_or_b32_e32 v34, s11, v3
	v_or_b32_e32 v35, s12, v2
	s_add_i32 s5, s5, 16
	s_add_i32 s1, s1, 16
	s_add_i32 s8, s8, -16
	v_or_b32_e32 v0, s12, v24
	v_or_b32_e32 v30, s11, v7
	v_lshlrev_b64 v[32:33], 12, v[0:1]
	v_lshlrev_b64 v[30:31], 12, v[30:31]
	v_lshl_add_u64 v[32:33], v[22:23], 0, v[32:33]
	v_lshl_add_u64 v[30:31], v[22:23], 0, v[30:31]
	global_load_dword v42, v[32:33], off
	global_load_dword v43, v[30:31], off
	v_mad_u64_u32 v[182:183], s[12:13], v35, s53, v[6:7]
	v_mad_u64_u32 v[184:185], s[12:13], v34, s53, v[6:7]
	s_add_i32 s12, s10, 8
	s_add_i32 s11, s9, 8
	v_mov_b32_e32 v31, v1
	v_or_b32_e32 v34, s11, v3
	v_or_b32_e32 v35, s12, v2
	v_or_b32_e32 v0, s12, v24
	v_or_b32_e32 v30, s11, v7
	v_lshlrev_b64 v[32:33], 12, v[0:1]
	v_lshlrev_b64 v[30:31], 12, v[30:31]
	v_lshl_add_u64 v[32:33], v[22:23], 0, v[32:33]
	v_lshl_add_u64 v[30:31], v[22:23], 0, v[30:31]
	global_load_dword v44, v[32:33], off
	global_load_dword v45, v[30:31], off
	v_mad_u64_u32 v[186:187], s[12:13], v35, s53, v[6:7]
	v_mad_u64_u32 v[188:189], s[12:13], v34, s53, v[6:7]
	s_add_i32 s12, s10, 12
	s_add_i32 s11, s9, 12
	v_mov_b32_e32 v31, v1
	v_or_b32_e32 v34, s11, v3
	v_or_b32_e32 v35, s12, v2
	v_or_b32_e32 v0, s12, v24
	v_or_b32_e32 v30, s11, v7
	v_lshlrev_b64 v[32:33], 12, v[0:1]
	v_lshlrev_b64 v[30:31], 12, v[30:31]
	v_lshl_add_u64 v[32:33], v[22:23], 0, v[32:33]
	v_lshl_add_u64 v[30:31], v[22:23], 0, v[30:31]
	global_load_dword v46, v[32:33], off
	global_load_dword v47, v[30:31], off
	v_mad_u64_u32 v[190:191], s[12:13], v35, s53, v[6:7]
	v_mad_u64_u32 v[192:193], s[12:13], v34, s53, v[6:7]
	s_add_i32 s12, s10, 16
	s_add_i32 s11, s9, 16
	v_mov_b32_e32 v31, v1
	v_or_b32_e32 v34, s11, v3
	v_or_b32_e32 v35, s12, v2
	v_or_b32_e32 v0, s12, v24
	v_or_b32_e32 v30, s11, v7
	v_lshlrev_b64 v[32:33], 12, v[0:1]
	v_lshlrev_b64 v[30:31], 12, v[30:31]
	v_lshl_add_u64 v[32:33], v[22:23], 0, v[32:33]
	v_lshl_add_u64 v[30:31], v[22:23], 0, v[30:31]
	global_load_dword v48, v[32:33], off
	global_load_dword v49, v[30:31], off
	v_mad_u64_u32 v[194:195], s[12:13], v35, s53, v[6:7]
	v_mad_u64_u32 v[196:197], s[12:13], v34, s53, v[6:7]
	s_add_i32 s12, s10, 20
	s_add_i32 s11, s9, 20
	v_mov_b32_e32 v31, v1
	v_or_b32_e32 v34, s11, v3
	v_or_b32_e32 v35, s12, v2
	v_or_b32_e32 v0, s12, v24
	v_or_b32_e32 v30, s11, v7
	v_lshlrev_b64 v[32:33], 12, v[0:1]
	v_lshlrev_b64 v[30:31], 12, v[30:31]
	v_lshl_add_u64 v[32:33], v[22:23], 0, v[32:33]
	v_lshl_add_u64 v[30:31], v[22:23], 0, v[30:31]
	global_load_dword v50, v[32:33], off
	global_load_dword v51, v[30:31], off
	v_mad_u64_u32 v[198:199], s[12:13], v35, s53, v[6:7]
	v_mad_u64_u32 v[200:201], s[12:13], v34, s53, v[6:7]
	s_add_i32 s12, s10, 24
	s_add_i32 s11, s9, 24
	v_mov_b32_e32 v31, v1
	v_or_b32_e32 v35, s12, v2
	v_or_b32_e32 v34, s11, v3
	s_add_i32 s10, s10, 28
	s_add_i32 s9, s9, 28
	s_cmp_lg_u32 s8, 0
	v_or_b32_e32 v0, s12, v24
	v_or_b32_e32 v30, s11, v7
	v_lshlrev_b64 v[32:33], 12, v[0:1]
	v_lshlrev_b64 v[30:31], 12, v[30:31]
	v_lshl_add_u64 v[32:33], v[22:23], 0, v[32:33]
	v_lshl_add_u64 v[30:31], v[22:23], 0, v[30:31]
	global_load_dword v52, v[32:33], off
	global_load_dword v53, v[30:31], off
	v_mad_u64_u32 v[202:203], s[12:13], v35, s53, v[6:7]
	v_mad_u64_u32 v[204:205], s[12:13], v34, s53, v[6:7]
	v_mov_b32_e32 v31, v1
	v_or_b32_e32 v35, s10, v2
	v_or_b32_e32 v34, s9, v3
	v_or_b32_e32 v0, s10, v24
	v_or_b32_e32 v30, s9, v7
	v_lshlrev_b64 v[32:33], 12, v[0:1]
	v_lshlrev_b64 v[30:31], 12, v[30:31]
	v_lshl_add_u64 v[32:33], v[22:23], 0, v[32:33]
	v_lshl_add_u64 v[30:31], v[22:23], 0, v[30:31]
	global_load_dword v54, v[32:33], off
	global_load_dword v55, v[30:31], off
	v_mad_u64_u32 v[206:207], s[10:11], v35, s53, v[6:7]
	v_mad_u64_u32 v[208:209], s[10:11], v34, s53, v[6:7]
	s_waitcnt vmcnt(0)
	ds_write_b32 v178, v40
	ds_write_b32 v180, v41
	ds_write_b32 v182, v42
	ds_write_b32 v184, v43
	ds_write_b32 v186, v44
	ds_write_b32 v188, v45
	ds_write_b32 v190, v46
	ds_write_b32 v192, v47
	ds_write_b32 v194, v48
	ds_write_b32 v196, v49
	ds_write_b32 v198, v50
	ds_write_b32 v200, v51
	ds_write_b32 v202, v52
	ds_write_b32 v204, v53
	ds_write_b32 v206, v54
	ds_write_b32 v208, v55
	s_cbranch_scc1 .LBB0_146
	s_waitcnt lgkmcnt(0)
	ds_read_b32 v0, v26
	ds_read_b32 v7, v26 offset:132
	s_lshl_b32 s88, s4, 1
	v_lshl_add_u64 v[22:23], v[18:19], 0, s[88:89]
	s_movk_i32 s88, 0xf400
	s_waitcnt lgkmcnt(0)
	v_cvt_pk_bf16_f32 v30, v0, v7
	ds_read_b32 v0, v26 offset:264
	ds_read_b32 v7, v26 offset:396
	s_waitcnt lgkmcnt(0)
	v_cvt_pk_bf16_f32 v31, v0, v7
	ds_read_b32 v0, v26 offset:528
	ds_read_b32 v7, v26 offset:660
	s_waitcnt lgkmcnt(0)
	v_cvt_pk_bf16_f32 v32, v0, v7
	ds_read_b32 v0, v26 offset:792
	ds_read_b32 v7, v26 offset:924
	s_waitcnt lgkmcnt(0)
	v_cvt_pk_bf16_f32 v33, v0, v7
	v_or_b32_e32 v0, s0, v25
	v_lshlrev_b32_e32 v0, 11, v0
	v_lshl_add_u64 v[34:35], v[22:23], 0, v[0:1]
	flat_store_dwordx4 v[34:35], v[30:33]
	ds_read_b32 v0, v26 offset:32
	ds_read_b32 v7, v26 offset:164
	s_waitcnt lgkmcnt(0)
	v_cvt_pk_bf16_f32 v30, v0, v7
	ds_read_b32 v0, v26 offset:296
	ds_read_b32 v7, v26 offset:428
	s_waitcnt lgkmcnt(0)
	v_cvt_pk_bf16_f32 v31, v0, v7
	ds_read_b32 v0, v26 offset:560
	ds_read_b32 v7, v26 offset:692
	s_waitcnt lgkmcnt(0)
	v_cvt_pk_bf16_f32 v32, v0, v7
	ds_read_b32 v0, v26 offset:824
	ds_read_b32 v7, v26 offset:956
	s_waitcnt lgkmcnt(0)
	v_cvt_pk_bf16_f32 v33, v0, v7
	v_or_b32_e32 v0, s0, v27
	v_lshlrev_b32_e32 v0, 11, v0
	v_lshl_add_u64 v[34:35], v[22:23], 0, v[0:1]
	flat_store_dwordx4 v[34:35], v[30:33]
	ds_read_b32 v0, v26 offset:64
	ds_read_b32 v7, v26 offset:196
	s_waitcnt lgkmcnt(0)
	v_cvt_pk_bf16_f32 v30, v0, v7
	ds_read_b32 v0, v26 offset:328
	ds_read_b32 v7, v26 offset:460
	s_waitcnt lgkmcnt(0)
	v_cvt_pk_bf16_f32 v31, v0, v7
	ds_read_b32 v0, v26 offset:592
	ds_read_b32 v7, v26 offset:724
	s_waitcnt lgkmcnt(0)
	v_cvt_pk_bf16_f32 v32, v0, v7
	ds_read_b32 v0, v26 offset:856
	ds_read_b32 v7, v26 offset:988
	s_waitcnt lgkmcnt(0)
	v_cvt_pk_bf16_f32 v33, v0, v7
	v_or_b32_e32 v0, s0, v28
	v_lshlrev_b32_e32 v0, 11, v0
	v_lshl_add_u64 v[34:35], v[22:23], 0, v[0:1]
	flat_store_dwordx4 v[34:35], v[30:33]
	ds_read_b32 v0, v26 offset:96
	ds_read_b32 v7, v26 offset:228
	s_waitcnt lgkmcnt(0)
	v_cvt_pk_bf16_f32 v30, v0, v7
	ds_read_b32 v0, v26 offset:360
	ds_read_b32 v7, v26 offset:492
	s_waitcnt lgkmcnt(0)
	v_cvt_pk_bf16_f32 v31, v0, v7
	ds_read_b32 v0, v26 offset:624
	ds_read_b32 v7, v26 offset:756
	s_waitcnt lgkmcnt(0)
	v_cvt_pk_bf16_f32 v32, v0, v7
	ds_read_b32 v0, v26 offset:888
	ds_read_b32 v7, v26 offset:1020
	s_waitcnt lgkmcnt(0)
	v_cvt_pk_bf16_f32 v33, v0, v7
	v_or_b32_e32 v0, s0, v29
	v_lshlrev_b32_e32 v0, 11, v0
	v_lshl_add_u64 v[22:23], v[22:23], 0, v[0:1]
	flat_store_dwordx4 v[22:23], v[30:33]
	s_waitcnt lgkmcnt(0)

.LBB0_151:
	s_lshl_b32 s10, s5, 1
	s_lshl_b32 s9, s1, 1
	v_or_b32_e32 v30, s10, v0
	v_or_b32_e32 v32, s9, v7
	v_mad_i64_i32 v[30:31], s[12:13], v30, s54, v[22:23]
	v_mad_i64_i32 v[32:33], s[12:13], v32, s54, v[22:23]
	global_load_dword v40, v[30:31], off
	global_load_dword v41, v[32:33], off
	v_or_b32_e32 v24, s9, v3
	v_or_b32_e32 v34, s10, v2
	v_mad_u64_u32 v[178:179], s[12:13], v34, s53, v[6:7]
	v_mad_u64_u32 v[180:181], s[12:13], v24, s53, v[6:7]
	s_add_i32 s12, s10, 4
	s_add_i32 s11, s9, 4
	v_or_b32_e32 v34, s12, v2
	v_or_b32_e32 v24, s11, v3
	s_add_i32 s5, s5, 16
	s_add_i32 s1, s1, 16
	s_add_i32 s8, s8, -16
	v_or_b32_e32 v30, s12, v0
	v_or_b32_e32 v32, s11, v7
	v_mad_i64_i32 v[30:31], s[12:13], v30, s54, v[22:23]
	v_mad_i64_i32 v[32:33], s[12:13], v32, s54, v[22:23]
	global_load_dword v42, v[30:31], off
	global_load_dword v43, v[32:33], off
	v_mad_u64_u32 v[182:183], s[12:13], v34, s53, v[6:7]
	v_mad_u64_u32 v[184:185], s[12:13], v24, s53, v[6:7]
	s_add_i32 s12, s10, 8
	s_add_i32 s11, s9, 8
	v_or_b32_e32 v34, s12, v2
	v_or_b32_e32 v24, s11, v3
	v_or_b32_e32 v30, s12, v0
	v_or_b32_e32 v32, s11, v7
	v_mad_i64_i32 v[30:31], s[12:13], v30, s54, v[22:23]
	v_mad_i64_i32 v[32:33], s[12:13], v32, s54, v[22:23]
	global_load_dword v44, v[30:31], off
	global_load_dword v45, v[32:33], off
	v_mad_u64_u32 v[186:187], s[12:13], v34, s53, v[6:7]
	v_mad_u64_u32 v[188:189], s[12:13], v24, s53, v[6:7]
	s_add_i32 s12, s10, 12
	s_add_i32 s11, s9, 12
	v_or_b32_e32 v34, s12, v2
	v_or_b32_e32 v24, s11, v3
	v_or_b32_e32 v30, s12, v0
	v_or_b32_e32 v32, s11, v7
	v_mad_i64_i32 v[30:31], s[12:13], v30, s54, v[22:23]
	v_mad_i64_i32 v[32:33], s[12:13], v32, s54, v[22:23]
	global_load_dword v46, v[30:31], off
	global_load_dword v47, v[32:33], off
	v_mad_u64_u32 v[190:191], s[12:13], v34, s53, v[6:7]
	v_mad_u64_u32 v[192:193], s[12:13], v24, s53, v[6:7]
	s_add_i32 s12, s10, 16
	s_add_i32 s11, s9, 16
	v_or_b32_e32 v34, s12, v2
	v_or_b32_e32 v24, s11, v3
	v_or_b32_e32 v30, s12, v0
	v_or_b32_e32 v32, s11, v7
	v_mad_i64_i32 v[30:31], s[12:13], v30, s54, v[22:23]
	v_mad_i64_i32 v[32:33], s[12:13], v32, s54, v[22:23]
	global_load_dword v48, v[30:31], off
	global_load_dword v49, v[32:33], off
	v_mad_u64_u32 v[194:195], s[12:13], v34, s53, v[6:7]
	v_mad_u64_u32 v[196:197], s[12:13], v24, s53, v[6:7]
	s_add_i32 s12, s10, 20
	s_add_i32 s11, s9, 20
	v_or_b32_e32 v34, s12, v2
	v_or_b32_e32 v24, s11, v3
	v_or_b32_e32 v30, s12, v0
	v_or_b32_e32 v32, s11, v7
	v_mad_i64_i32 v[30:31], s[12:13], v30, s54, v[22:23]
	v_mad_i64_i32 v[32:33], s[12:13], v32, s54, v[22:23]
	global_load_dword v50, v[30:31], off
	global_load_dword v51, v[32:33], off
	v_mad_u64_u32 v[198:199], s[12:13], v34, s53, v[6:7]
	v_mad_u64_u32 v[200:201], s[12:13], v24, s53, v[6:7]
	s_add_i32 s12, s10, 24
	s_add_i32 s11, s9, 24
	v_or_b32_e32 v34, s12, v2
	v_or_b32_e32 v24, s11, v3
	s_add_i32 s10, s10, 28
	s_add_i32 s9, s9, 28
	s_cmp_lg_u32 s8, 0
	v_or_b32_e32 v30, s12, v0
	v_or_b32_e32 v32, s11, v7
	v_mad_i64_i32 v[30:31], s[12:13], v30, s54, v[22:23]
	v_mad_i64_i32 v[32:33], s[12:13], v32, s54, v[22:23]
	global_load_dword v52, v[30:31], off
	global_load_dword v53, v[32:33], off
	v_mad_u64_u32 v[202:203], s[12:13], v34, s53, v[6:7]
	v_mad_u64_u32 v[204:205], s[12:13], v24, s53, v[6:7]
	v_or_b32_e32 v34, s10, v2
	v_or_b32_e32 v24, s9, v3
	v_or_b32_e32 v30, s10, v0
	v_or_b32_e32 v32, s9, v7
	v_mad_i64_i32 v[30:31], s[10:11], v30, s54, v[22:23]
	v_mad_i64_i32 v[32:33], s[10:11], v32, s54, v[22:23]
	global_load_dword v54, v[30:31], off
	global_load_dword v55, v[32:33], off
	v_mad_u64_u32 v[206:207], s[10:11], v34, s53, v[6:7]
	v_mad_u64_u32 v[208:209], s[10:11], v24, s53, v[6:7]
	s_waitcnt vmcnt(0)
	ds_write_b32 v178, v40
	ds_write_b32 v180, v41
	ds_write_b32 v182, v42
	ds_write_b32 v184, v43
	ds_write_b32 v186, v44
	ds_write_b32 v188, v45
	ds_write_b32 v190, v46
	ds_write_b32 v192, v47
	ds_write_b32 v194, v48
	ds_write_b32 v196, v49
	ds_write_b32 v198, v50
	ds_write_b32 v200, v51
	ds_write_b32 v202, v52
	ds_write_b32 v204, v53
	ds_write_b32 v206, v54
	ds_write_b32 v208, v55
	s_cbranch_scc1 .LBB0_151
	s_waitcnt lgkmcnt(0)
	ds_read_b32 v0, v26
	ds_read_b32 v7, v26 offset:132
	v_or_b32_e32 v34, s0, v25
	s_ashr_i32 s5, s4, 31
	v_ashrrev_i32_e32 v35, 31, v34
	v_lshl_add_u64 v[22:23], s[4:5], 1, v[8:9]
	s_waitcnt lgkmcnt(0)
	v_cvt_pk_bf16_f32 v30, v0, v7
	ds_read_b32 v0, v26 offset:264
	ds_read_b32 v7, v26 offset:396
	v_lshlrev_b64 v[34:35], 11, v[34:35]
	v_lshl_add_u64 v[34:35], v[22:23], 0, v[34:35]
	s_waitcnt lgkmcnt(0)
	v_cvt_pk_bf16_f32 v31, v0, v7
	ds_read_b32 v0, v26 offset:528
	ds_read_b32 v7, v26 offset:660
	s_waitcnt lgkmcnt(0)
	v_cvt_pk_bf16_f32 v32, v0, v7
	ds_read_b32 v0, v26 offset:792
	ds_read_b32 v7, v26 offset:924
	s_waitcnt lgkmcnt(0)
	v_cvt_pk_bf16_f32 v33, v0, v7
	flat_store_dwordx4 v[34:35], v[30:33]
	ds_read_b32 v0, v26 offset:32
	ds_read_b32 v7, v26 offset:164
	v_or_b32_e32 v34, s0, v27
	v_ashrrev_i32_e32 v35, 31, v34
	v_lshlrev_b64 v[34:35], 11, v[34:35]
	v_lshl_add_u64 v[34:35], v[22:23], 0, v[34:35]
	s_waitcnt lgkmcnt(0)
	v_cvt_pk_bf16_f32 v30, v0, v7
	ds_read_b32 v0, v26 offset:296
	ds_read_b32 v7, v26 offset:428
	s_waitcnt lgkmcnt(0)
	v_cvt_pk_bf16_f32 v31, v0, v7
	ds_read_b32 v0, v26 offset:560
	ds_read_b32 v7, v26 offset:692
	s_waitcnt lgkmcnt(0)
	v_cvt_pk_bf16_f32 v32, v0, v7
	ds_read_b32 v0, v26 offset:824
	ds_read_b32 v7, v26 offset:956
	s_waitcnt lgkmcnt(0)
	v_cvt_pk_bf16_f32 v33, v0, v7
	flat_store_dwordx4 v[34:35], v[30:33]
	ds_read_b32 v0, v26 offset:64
	ds_read_b32 v7, v26 offset:196
	v_or_b32_e32 v34, s0, v28
	v_ashrrev_i32_e32 v35, 31, v34
	v_lshlrev_b64 v[34:35], 11, v[34:35]
	v_lshl_add_u64 v[34:35], v[22:23], 0, v[34:35]
	s_waitcnt lgkmcnt(0)
	v_cvt_pk_bf16_f32 v30, v0, v7
	ds_read_b32 v0, v26 offset:328
	ds_read_b32 v7, v26 offset:460
	s_waitcnt lgkmcnt(0)
	v_cvt_pk_bf16_f32 v31, v0, v7
	ds_read_b32 v0, v26 offset:592
	ds_read_b32 v7, v26 offset:724
	s_waitcnt lgkmcnt(0)
	v_cvt_pk_bf16_f32 v32, v0, v7
	ds_read_b32 v0, v26 offset:856
	ds_read_b32 v7, v26 offset:988
	s_waitcnt lgkmcnt(0)
	v_cvt_pk_bf16_f32 v33, v0, v7
	flat_store_dwordx4 v[34:35], v[30:33]
	ds_read_b32 v0, v26 offset:96
	ds_read_b32 v7, v26 offset:228
	v_or_b32_e32 v34, s0, v29
	v_ashrrev_i32_e32 v35, 31, v34
	v_lshlrev_b64 v[34:35], 11, v[34:35]
	v_lshl_add_u64 v[22:23], v[22:23], 0, v[34:35]
	s_waitcnt lgkmcnt(0)
	v_cvt_pk_bf16_f32 v30, v0, v7
	ds_read_b32 v0, v26 offset:360
	ds_read_b32 v7, v26 offset:492
	s_waitcnt lgkmcnt(0)
	v_cvt_pk_bf16_f32 v31, v0, v7
	ds_read_b32 v0, v26 offset:624
	ds_read_b32 v7, v26 offset:756
	s_waitcnt lgkmcnt(0)
	v_cvt_pk_bf16_f32 v32, v0, v7
	ds_read_b32 v0, v26 offset:888
	ds_read_b32 v7, v26 offset:1020
	s_waitcnt lgkmcnt(0)
	v_cvt_pk_bf16_f32 v33, v0, v7
	flat_store_dwordx4 v[22:23], v[30:33]
	s_waitcnt lgkmcnt(0)
	s_branch .LBB0_132
